# GEMM1 epilogue: nt policy on the z (bf16) tile stores (placement test of cache policy for the 517 MB streamed output)
# speedup vs baseline: 1.0213x; 1.0213x over previous
; #define PG8_STAGE(bufoff, gbase, voff) do { _Pragma("unroll") for (int _i = 0; _i < 2; ++_i) \
;         __builtin_amdgcn_global_load_lds((const unsigned*)((const char*)(gbase) + (voff)[_i]), (LAS unsigned*)(lds + (bufoff) + ldsw + _i * 8192), 16, 0, 0); } while (0)
; #define PG8_LDA(dst, b, h) do { _Pragma("unroll") for (int m = 0; m < 4; ++m) _Pragma("unroll") for (int k = 0; k < 2; ++k) dst[m][k] = *(const LAS bf16x8*)(lds + PG8_SA(b, h) + aoff + m * 2048 + k * 1024); } while (0)
; #define PG8_LDB(dst, b, h) do { _Pragma("unroll") for (int n = 0; n < 2; ++n) _Pragma("unroll") for (int k = 0; k < 2; ++k) dst[n][k] = *(const LAS bf16x8*)(lds + PG8_SB(b, h) + boff + n * 2048 + k * 1024); } while (0)
; #define PG8_MMA(ai, bj, At, Bt) do { __builtin_amdgcn_s_setprio(1); _Pragma("unroll") for (int m = 0; m < 4; ++m) _Pragma("unroll") for (int n = 0; n < 2; ++n) _Pragma("unroll") for (int k = 0; k < 2; ++k) \
;         acc[ai][bj][m][n] = __builtin_amdgcn_mfma_f32_16x16x32_bf16(Bt[n][k], At[m][k], acc[ai][bj][m][n], 0, 0, 0); __builtin_amdgcn_s_setprio(0); } while (0)
; #define PG8_WAIT_L(n) asm volatile("s_waitcnt lgkmcnt(" #n ")" ::: "memory")
; #define PG8_BAR __builtin_amdgcn_s_barrier()
; #define PG8_SCHED __builtin_amdgcn_sched_barrier(0)
; template <class Epi>
; __device__ __forceinline__ void gemm_phase(LAS unsigned char* lds, const Gemm g, const StaticOrder& S, const Epi& E) {
;     ...
;         for (int t = 0; t < nt; t += 2) {
;             const bool last = (t == nt - 2);
;             const char* a1 = cA + (size_t)(t + 1) * kstep;
;             const char* a2 = last ? nA : cA + (size_t)(t + 2) * kstep; const char* b2 = last ? nB : cB + (size_t)(t + 2) * kstep;
;             const char* a3 = a2 + kstep; const char* b3 = b2 + kstep;
;             PG8_LDB(B0, 0, 0); PG8_SCHED; PG8_LDA(At, 0, 0); PG8_STAGE(PG8_SA(1, 1), a1 + hstep, voffA);
;             PG8_WAIT_L(8); PG8_BAR; PG8_WAIT_L(0); PG8_MMA(0, 0, At, B0); PG8_BAR; PG8_SCHED;
;             PG8_LDB(B1, 0, 1); PG8_STAGE(PG8_SB(0, 0), b2, voffB);
;             PG8_BAR; PG8_WAIT_L(0); PG8_MMA(0, 1, At, B1); PG8_BAR;
;             PG8_LDA(At, 0, 1); PG8_STAGE(PG8_SA(0, 0), a2, voffA);
;             PG8_BAR; PG8_WAIT_L(0); PG8_MMA(1, 0, At, B0); PG8_BAR; PG8_SCHED;
.LBB0_80:
	ds_read_b128 v[154:157], v173
	ds_read_b128 v[176:179], v173 offset:1024
	ds_read_b128 v[180:183], v173 offset:2048
	ds_read_b128 v[184:187], v173 offset:3072
	s_add_u32 s26, s12, 0xfff80080
	s_addc_u32 s27, s13, -1
	s_cmp_eq_u32 s67, 28
	s_cselect_b32 s29, s7, s27
	s_cselect_b32 s28, s63, s26
	s_cselect_b32 s27, s25, s66
	s_cselect_b32 s26, s64, s65
	v_lshl_add_u64 v[220:221], s[12:13], 0, v[146:147]
	s_add_i32 m0, s42, 0xc000
	ds_read_b128 v[188:191], v174
	ds_read_b128 v[192:195], v174 offset:1024
	ds_read_b128 v[196:199], v174 offset:2048
	ds_read_b128 v[200:203], v174 offset:3072
	ds_read_b128 v[204:207], v174 offset:4096
	ds_read_b128 v[208:211], v174 offset:5120
	ds_read_b128 v[212:215], v174 offset:6144
	ds_read_b128 v[216:219], v174 offset:7168
	global_load_lds_dwordx4 v[220:221], off
	v_lshl_add_u64 v[220:221], s[12:13], 0, v[148:149]
	s_add_i32 m0, s42, 0xe000
	s_nop 0
	global_load_lds_dwordx4 v[220:221], off
	s_waitcnt lgkmcnt(8)
	s_barrier
	s_waitcnt lgkmcnt(0)
	s_setprio 1
	s_waitcnt lgkmcnt(0)
	v_mfma_f32_16x16x32_bf16 v[124:127], v[154:157], v[188:191], v[124:127]
	v_mfma_f32_16x16x32_bf16 v[120:123], v[180:183], v[188:191], v[120:123]
	v_mfma_f32_16x16x32_bf16 v[116:119], v[154:157], v[196:199], v[116:119]
	v_mfma_f32_16x16x32_bf16 v[112:115], v[180:183], v[196:199], v[112:115]
	v_mfma_f32_16x16x32_bf16 v[100:103], v[154:157], v[204:207], v[100:103]
	v_mfma_f32_16x16x32_bf16 v[96:99], v[180:183], v[204:207], v[96:99]
	v_mfma_f32_16x16x32_bf16 v[76:79], v[154:157], v[212:215], v[76:79]
	v_mfma_f32_16x16x32_bf16 v[72:75], v[180:183], v[212:215], v[72:75]
	v_mfma_f32_16x16x32_bf16 v[124:127], v[176:179], v[192:195], v[124:127]
	v_mfma_f32_16x16x32_bf16 v[120:123], v[184:187], v[192:195], v[120:123]
	v_mfma_f32_16x16x32_bf16 v[116:119], v[176:179], v[200:203], v[116:119]
	v_mfma_f32_16x16x32_bf16 v[112:115], v[184:187], v[200:203], v[112:115]
	v_mfma_f32_16x16x32_bf16 v[100:103], v[176:179], v[208:211], v[100:103]
	v_mfma_f32_16x16x32_bf16 v[96:99], v[184:187], v[208:211], v[96:99]
	v_mfma_f32_16x16x32_bf16 v[76:79], v[176:179], v[216:219], v[76:79]
	v_mfma_f32_16x16x32_bf16 v[72:75], v[184:187], v[216:219], v[72:75]
	s_setprio 0
	s_barrier
	s_add_i32 s68, s55, s35
	v_lshl_add_u64 v[236:237], s[26:27], 0, v[140:141]
	s_mov_b32 m0, s68
	ds_read_b128 v[220:223], v175
	ds_read_b128 v[224:227], v175 offset:1024
	ds_read_b128 v[228:231], v175 offset:2048
	ds_read_b128 v[232:235], v175 offset:3072
	global_load_lds_dwordx4 v[236:237], off
	v_lshl_add_u64 v[238:239], s[26:27], 0, v[136:137]
	s_add_i32 m0, s68, 0x2000
	s_nop 0
	global_load_lds_dwordx4 v[238:239], off
	s_barrier
	s_waitcnt lgkmcnt(0)
	s_setprio 1
	s_waitcnt lgkmcnt(0)
	v_mfma_f32_16x16x32_bf16 v[108:111], v[220:223], v[188:191], v[108:111]
	v_mfma_f32_16x16x32_bf16 v[104:107], v[228:231], v[188:191], v[104:107]
	v_mfma_f32_16x16x32_bf16 v[92:95], v[220:223], v[196:199], v[92:95]
	v_mfma_f32_16x16x32_bf16 v[88:91], v[228:231], v[196:199], v[88:91]
	v_mfma_f32_16x16x32_bf16 v[84:87], v[220:223], v[204:207], v[84:87]
	v_mfma_f32_16x16x32_bf16 v[80:83], v[228:231], v[204:207], v[80:83]
	v_mfma_f32_16x16x32_bf16 v[68:71], v[220:223], v[212:215], v[68:71]
	v_mfma_f32_16x16x32_bf16 v[64:67], v[228:231], v[212:215], v[64:67]
	v_mfma_f32_16x16x32_bf16 v[108:111], v[224:227], v[192:195], v[108:111]
	v_mfma_f32_16x16x32_bf16 v[104:107], v[232:235], v[192:195], v[104:107]
	v_mfma_f32_16x16x32_bf16 v[92:95], v[224:227], v[200:203], v[92:95]
	v_mfma_f32_16x16x32_bf16 v[88:91], v[232:235], v[200:203], v[88:91]
	v_mfma_f32_16x16x32_bf16 v[84:87], v[224:227], v[208:211], v[84:87]
	v_mfma_f32_16x16x32_bf16 v[80:83], v[232:235], v[208:211], v[80:83]
	v_mfma_f32_16x16x32_bf16 v[68:71], v[224:227], v[216:219], v[68:71]
	v_mfma_f32_16x16x32_bf16 v[64:67], v[232:235], v[216:219], v[64:67]
	s_setprio 0
	s_mov_b32 m0, s42
	v_lshl_add_u64 v[240:241], s[28:29], 0, v[142:143]
	s_barrier
	ds_read_b128 v[188:191], v174 offset:16384
	ds_read_b128 v[192:195], v174 offset:17408
	ds_read_b128 v[196:199], v174 offset:18432
	ds_read_b128 v[200:203], v174 offset:19456
	ds_read_b128 v[204:207], v174 offset:20480
	ds_read_b128 v[208:211], v174 offset:21504
	ds_read_b128 v[212:215], v174 offset:22528
	ds_read_b128 v[216:219], v174 offset:23552
	global_load_lds_dwordx4 v[240:241], off
	v_lshl_add_u64 v[242:243], s[28:29], 0, v[138:139]
	s_mov_b32 m0, s43
	s_nop 0
	global_load_lds_dwordx4 v[242:243], off
	s_barrier
	s_waitcnt lgkmcnt(0)
	s_setprio 1
	s_waitcnt lgkmcnt(0)
	v_mfma_f32_16x16x32_bf16 v[60:63], v[154:157], v[188:191], v[60:63]
	v_mfma_f32_16x16x32_bf16 v[56:59], v[180:183], v[188:191], v[56:59]
	v_mfma_f32_16x16x32_bf16 v[52:55], v[154:157], v[196:199], v[52:55]
	v_mfma_f32_16x16x32_bf16 v[48:51], v[180:183], v[196:199], v[48:51]
	v_mfma_f32_16x16x32_bf16 v[36:39], v[154:157], v[204:207], v[36:39]
	v_mfma_f32_16x16x32_bf16 v[32:35], v[180:183], v[204:207], v[32:35]
	v_mfma_f32_16x16x32_bf16 v[12:15], v[154:157], v[212:215], v[12:15]
	v_mfma_f32_16x16x32_bf16 v[8:11], v[180:183], v[212:215], v[8:11]
	v_mfma_f32_16x16x32_bf16 v[60:63], v[176:179], v[192:195], v[60:63]
	v_mfma_f32_16x16x32_bf16 v[56:59], v[184:187], v[192:195], v[56:59]
	v_mfma_f32_16x16x32_bf16 v[52:55], v[176:179], v[200:203], v[52:55]
	v_mfma_f32_16x16x32_bf16 v[48:51], v[184:187], v[200:203], v[48:51]
	v_mfma_f32_16x16x32_bf16 v[36:39], v[176:179], v[208:211], v[36:39]
	v_mfma_f32_16x16x32_bf16 v[32:35], v[184:187], v[208:211], v[32:35]
	v_mfma_f32_16x16x32_bf16 v[12:15], v[176:179], v[216:219], v[12:15]
	v_mfma_f32_16x16x32_bf16 v[8:11], v[184:187], v[216:219], v[8:11]
	s_setprio 0
	s_barrier
; #define PG8_STAGE(bufoff, gbase, voff) do { _Pragma("unroll") for (int _i = 0; _i < 2; ++_i) \
;         __builtin_amdgcn_global_load_lds((const unsigned*)((const char*)(gbase) + (voff)[_i]), (LAS unsigned*)(lds + (bufoff) + ldsw + _i * 8192), 16, 0, 0); } while (0)
; #define PG8_LDA(dst, b, h) do { _Pragma("unroll") for (int m = 0; m < 4; ++m) _Pragma("unroll") for (int k = 0; k < 2; ++k) dst[m][k] = *(const LAS bf16x8*)(lds + PG8_SA(b, h) + aoff + m * 2048 + k * 1024); } while (0)
; #define PG8_LDB(dst, b, h) do { _Pragma("unroll") for (int n = 0; n < 2; ++n) _Pragma("unroll") for (int k = 0; k < 2; ++k) dst[n][k] = *(const LAS bf16x8*)(lds + PG8_SB(b, h) + boff + n * 2048 + k * 1024); } while (0)
; #define PG8_MMA(ai, bj, At, Bt) do { __builtin_amdgcn_s_setprio(1); _Pragma("unroll") for (int m = 0; m < 4; ++m) _Pragma("unroll") for (int n = 0; n < 2; ++n) _Pragma("unroll") for (int k = 0; k < 2; ++k) \
;         acc[ai][bj][m][n] = __builtin_amdgcn_mfma_f32_16x16x32_bf16(Bt[n][k], At[m][k], acc[ai][bj][m][n], 0, 0, 0); __builtin_amdgcn_s_setprio(0); } while (0)
; #define PG8_WAIT_V(n) asm volatile("s_waitcnt vmcnt(" #n ")" ::: "memory")
; #define PG8_WAIT_L(n) asm volatile("s_waitcnt lgkmcnt(" #n ")" ::: "memory")
; #define PG8_BAR __builtin_amdgcn_s_barrier()
; #define PG8_SCHED __builtin_amdgcn_sched_barrier(0)
; template <class Epi>
; __device__ __forceinline__ void gemm_phase(LAS unsigned char* lds, const Gemm g, const StaticOrder& S, const Epi& E) {
;     ...
;             PG8_STAGE(PG8_SB(0, 1), b2 + hstep, voffB);
;             PG8_WAIT_V(6); PG8_BAR; PG8_MMA(1, 1, At, B1); PG8_BAR;
;             PG8_LDB(B0, 1, 0); PG8_SCHED; PG8_LDA(At, 1, 0); PG8_STAGE(PG8_SA(0, 1), a2 + hstep, voffA);
;             PG8_WAIT_L(8); PG8_BAR; PG8_WAIT_L(0); PG8_MMA(0, 0, At, B0); PG8_BAR; PG8_SCHED;
;             PG8_LDB(B1, 1, 1); PG8_STAGE(PG8_SB(1, 0), b3, voffB);
;             PG8_BAR; PG8_WAIT_L(0); PG8_MMA(0, 1, At, B1); PG8_BAR;
;             PG8_LDA(At, 1, 1); PG8_STAGE(PG8_SA(1, 0), a3, voffA);
	s_add_u32 s68, s26, 0x80000
	s_addc_u32 s69, s27, 0
	s_add_i32 s70, s56, s35
	v_lshl_add_u64 v[154:155], s[68:69], 0, v[140:141]
	s_mov_b32 m0, s70
	s_nop 0
	global_load_lds_dwordx4 v[154:155], off
	v_lshl_add_u64 v[154:155], s[68:69], 0, v[136:137]
	s_add_i32 m0, s70, 0x2000
	s_nop 0
	global_load_lds_dwordx4 v[154:155], off
	s_waitcnt vmcnt(6)
	s_barrier
	s_setprio 1
	v_mfma_f32_16x16x32_bf16 v[44:47], v[220:223], v[188:191], v[44:47]
	v_mfma_f32_16x16x32_bf16 v[40:43], v[228:231], v[188:191], v[40:43]
	v_mfma_f32_16x16x32_bf16 v[28:31], v[220:223], v[196:199], v[28:31]
	v_mfma_f32_16x16x32_bf16 v[24:27], v[228:231], v[196:199], v[24:27]
	v_mfma_f32_16x16x32_bf16 v[20:23], v[220:223], v[204:207], v[20:23]
	v_mfma_f32_16x16x32_bf16 v[16:19], v[228:231], v[204:207], v[16:19]
	v_mfma_f32_16x16x32_bf16 v[4:7], v[220:223], v[212:215], v[4:7]
	v_mfma_f32_16x16x32_bf16 v[0:3], v[228:231], v[212:215], v[0:3]
	v_mfma_f32_16x16x32_bf16 v[44:47], v[224:227], v[192:195], v[44:47]
	v_mfma_f32_16x16x32_bf16 v[40:43], v[232:235], v[192:195], v[40:43]
	v_mfma_f32_16x16x32_bf16 v[28:31], v[224:227], v[200:203], v[28:31]
	v_mfma_f32_16x16x32_bf16 v[24:27], v[232:235], v[200:203], v[24:27]
	v_mfma_f32_16x16x32_bf16 v[20:23], v[224:227], v[208:211], v[20:23]
	v_mfma_f32_16x16x32_bf16 v[16:19], v[232:235], v[208:211], v[16:19]
	v_mfma_f32_16x16x32_bf16 v[4:7], v[224:227], v[216:219], v[4:7]
	v_mfma_f32_16x16x32_bf16 v[0:3], v[232:235], v[216:219], v[0:3]
	s_setprio 0
	s_add_i32 s68, 0, 0x18000
	v_add_u32_e32 v144, s68, v135
	s_barrier
	ds_read_b128 v[154:157], v144
	ds_read_b128 v[176:179], v144 offset:1024
	ds_read_b128 v[180:183], v144 offset:2048
	ds_read_b128 v[184:187], v144 offset:3072
	s_add_u32 s28, s28, 0x80000
	s_addc_u32 s29, s29, 0
	s_mov_b32 m0, s44
	v_lshl_add_u64 v[220:221], s[28:29], 0, v[142:143]
	ds_read_b128 v[188:191], v174 offset:32768
	ds_read_b128 v[192:195], v174 offset:33792
	ds_read_b128 v[196:199], v174 offset:34816
	ds_read_b128 v[200:203], v174 offset:35840
	ds_read_b128 v[204:207], v174 offset:36864
	ds_read_b128 v[208:211], v174 offset:37888
	ds_read_b128 v[212:215], v174 offset:38912
	ds_read_b128 v[216:219], v174 offset:39936
	global_load_lds_dwordx4 v[220:221], off
	v_lshl_add_u64 v[220:221], s[28:29], 0, v[138:139]
	s_mov_b32 m0, s45
	s_nop 0
	global_load_lds_dwordx4 v[220:221], off
	s_waitcnt lgkmcnt(8)
	s_barrier
	s_waitcnt lgkmcnt(0)
	s_setprio 1
	s_waitcnt lgkmcnt(0)
	v_mfma_f32_16x16x32_bf16 v[124:127], v[154:157], v[188:191], v[124:127]
	v_mfma_f32_16x16x32_bf16 v[120:123], v[180:183], v[188:191], v[120:123]
	v_mfma_f32_16x16x32_bf16 v[116:119], v[154:157], v[196:199], v[116:119]
	v_mfma_f32_16x16x32_bf16 v[112:115], v[180:183], v[196:199], v[112:115]
	v_mfma_f32_16x16x32_bf16 v[100:103], v[154:157], v[204:207], v[100:103]
	v_mfma_f32_16x16x32_bf16 v[96:99], v[180:183], v[204:207], v[96:99]
	v_mfma_f32_16x16x32_bf16 v[76:79], v[154:157], v[212:215], v[76:79]
	v_mfma_f32_16x16x32_bf16 v[72:75], v[180:183], v[212:215], v[72:75]
	v_mfma_f32_16x16x32_bf16 v[124:127], v[176:179], v[192:195], v[124:127]
	v_mfma_f32_16x16x32_bf16 v[120:123], v[184:187], v[192:195], v[120:123]
	v_mfma_f32_16x16x32_bf16 v[116:119], v[176:179], v[200:203], v[116:119]
	v_mfma_f32_16x16x32_bf16 v[112:115], v[184:187], v[200:203], v[112:115]
	v_mfma_f32_16x16x32_bf16 v[100:103], v[176:179], v[208:211], v[100:103]
	v_mfma_f32_16x16x32_bf16 v[96:99], v[184:187], v[208:211], v[96:99]
	v_mfma_f32_16x16x32_bf16 v[76:79], v[176:179], v[216:219], v[76:79]
	v_mfma_f32_16x16x32_bf16 v[72:75], v[184:187], v[216:219], v[72:75]
	s_setprio 0
	s_barrier
	s_add_i32 s28, 0, 0x1c000
	s_add_i32 s29, s68, s35
	v_add_u32_e32 v144, s28, v135
	v_lshl_add_u64 v[236:237], v[236:237], 0, s[16:17]
	s_mov_b32 m0, s29
	ds_read_b128 v[220:223], v144
	ds_read_b128 v[224:227], v144 offset:1024
	ds_read_b128 v[228:231], v144 offset:2048
	ds_read_b128 v[232:235], v144 offset:3072
	global_load_lds_dwordx4 v[236:237], off
	v_lshl_add_u64 v[236:237], v[238:239], 0, s[16:17]
	s_add_i32 m0, s29, 0x2000
	s_nop 0
	global_load_lds_dwordx4 v[236:237], off
	s_barrier
	s_waitcnt lgkmcnt(0)
	s_setprio 1
	s_waitcnt lgkmcnt(0)
	v_mfma_f32_16x16x32_bf16 v[108:111], v[220:223], v[188:191], v[108:111]
	v_mfma_f32_16x16x32_bf16 v[104:107], v[228:231], v[188:191], v[104:107]
	v_mfma_f32_16x16x32_bf16 v[92:95], v[220:223], v[196:199], v[92:95]
	v_mfma_f32_16x16x32_bf16 v[88:91], v[228:231], v[196:199], v[88:91]
	v_mfma_f32_16x16x32_bf16 v[84:87], v[220:223], v[204:207], v[84:87]
	v_mfma_f32_16x16x32_bf16 v[80:83], v[228:231], v[204:207], v[80:83]
	v_mfma_f32_16x16x32_bf16 v[68:71], v[220:223], v[212:215], v[68:71]
	v_mfma_f32_16x16x32_bf16 v[64:67], v[228:231], v[212:215], v[64:67]
	v_mfma_f32_16x16x32_bf16 v[108:111], v[224:227], v[192:195], v[108:111]
	v_mfma_f32_16x16x32_bf16 v[104:107], v[232:235], v[192:195], v[104:107]
	v_mfma_f32_16x16x32_bf16 v[92:95], v[224:227], v[200:203], v[92:95]
	v_mfma_f32_16x16x32_bf16 v[88:91], v[232:235], v[200:203], v[88:91]
	v_mfma_f32_16x16x32_bf16 v[84:87], v[224:227], v[208:211], v[84:87]
	v_mfma_f32_16x16x32_bf16 v[80:83], v[232:235], v[208:211], v[80:83]
	v_mfma_f32_16x16x32_bf16 v[68:71], v[224:227], v[216:219], v[68:71]
	v_mfma_f32_16x16x32_bf16 v[64:67], v[232:235], v[216:219], v[64:67]
	s_setprio 0
	s_mov_b32 m0, s48
	v_lshl_add_u64 v[236:237], v[240:241], 0, s[16:17]
	s_barrier
	ds_read_b128 v[188:191], v174 offset:49152
	ds_read_b128 v[192:195], v174 offset:50176
	ds_read_b128 v[196:199], v174 offset:51200
	ds_read_b128 v[200:203], v174 offset:52224
	ds_read_b128 v[204:207], v174 offset:53248
	ds_read_b128 v[208:211], v174 offset:54272
	ds_read_b128 v[212:215], v174 offset:55296
	ds_read_b128 v[216:219], v174 offset:56320
	global_load_lds_dwordx4 v[236:237], off
	v_lshl_add_u64 v[236:237], v[242:243], 0, s[16:17]
	s_mov_b32 m0, s49
	s_nop 0
	global_load_lds_dwordx4 v[236:237], off
	s_barrier
; __device__ __forceinline__ unsigned pk_bf16(float lo, float hi) { const f32x2 v = (f32x2){lo, hi}; const bf16v2 b = __builtin_convertvector(v, bf16v2); return __builtin_bit_cast(unsigned, b); }
; #define PG8_STAGE(bufoff, gbase, voff) do { _Pragma("unroll") for (int _i = 0; _i < 2; ++_i) \
;         __builtin_amdgcn_global_load_lds((const unsigned*)((const char*)(gbase) + (voff)[_i]), (LAS unsigned*)(lds + (bufoff) + ldsw + _i * 8192), 16, 0, 0); } while (0)
; #define PG8_WAIT_V(n) asm volatile("s_waitcnt vmcnt(" #n ")" ::: "memory")
; #define PG8_WAIT_L(n) asm volatile("s_waitcnt lgkmcnt(" #n ")" ::: "memory")
; #define PG8_BAR __builtin_amdgcn_s_barrier()
; template <class Epi>
; __device__ __forceinline__ void gemm_phase(LAS unsigned char* lds, const Gemm g, const StaticOrder& S, const Epi& E) {
;     ...
;             PG8_BAR; PG8_WAIT_L(0); PG8_MMA(1, 0, At, B0); PG8_BAR; PG8_SCHED;
;             PG8_STAGE(PG8_SB(1, 1), b3 + hstep, voffB);
;             PG8_WAIT_V(6); PG8_BAR; PG8_MMA(1, 1, At, B1); PG8_BAR;
;     __device__ __forceinline__ void operator()(const f32x4 (&acc)[2][2][4][2], const pg8::Unit& u, int wr, int wc, int fr, int fq) const {
;         const int row0 = u.pm * 256 + wr * 64 + fr, col0 = u.pn * 256 + wc * 32 + 8 * fq;
; #pragma unroll
;         for (int ai = 0; ai < 2; ++ai)
; #pragma unroll
;             for (int m = 0; m < 4; ++m) {
;                 const int row = row0 + ai * 128 + m * 16;
;                 bf16_t* rowp = Z + (size_t)row * LDZ + col0;
;                 const bool last = ((row & 63) == 63) && (row >= MP || (row & (SEQ - 1)) == SEQ - 1);
; #pragma unroll
;                 for (int bj = 0; bj < 2; ++bj) {
;                     const f32x4 v0 = acc[ai][bj][m][0], v1 = acc[ai][bj][m][1];
;                     u32x4 w; w.x = pk_bf16(v0[0], v0[1]); w.y = pk_bf16(v0[2], v0[3]); w.z = pk_bf16(v1[0], v1[1]); w.w = pk_bf16(v1[2], v1[3]);
;                     *(u32x4*)(rowp + bj * 128) = w;
;                     if (last) {
;                         const int c = col0 + bj * 128 - ZC_S;
;                         if (c >= 0 && c < NSHIFT) {
;                             float* o = row < MP ? out + O_SHP + (size_t)(row >> 13) * NSHIFT + c : out + O_SHS + (size_t)((row - MP) >> 6) * NSHIFT + c;
;                             *(f32x4*)o = v0; *(f32x4*)(o + 4) = v1;
;                         }
;                     }
	s_waitcnt lgkmcnt(0)
	s_setprio 1
	s_waitcnt lgkmcnt(0)
	v_mfma_f32_16x16x32_bf16 v[60:63], v[154:157], v[188:191], v[60:63]
	v_mfma_f32_16x16x32_bf16 v[56:59], v[180:183], v[188:191], v[56:59]
	v_mfma_f32_16x16x32_bf16 v[52:55], v[154:157], v[196:199], v[52:55]
	v_mfma_f32_16x16x32_bf16 v[48:51], v[180:183], v[196:199], v[48:51]
	v_mfma_f32_16x16x32_bf16 v[36:39], v[154:157], v[204:207], v[36:39]
	v_mfma_f32_16x16x32_bf16 v[32:35], v[180:183], v[204:207], v[32:35]
	v_mfma_f32_16x16x32_bf16 v[12:15], v[154:157], v[212:215], v[12:15]
	v_mfma_f32_16x16x32_bf16 v[8:11], v[180:183], v[212:215], v[8:11]
	v_mfma_f32_16x16x32_bf16 v[60:63], v[176:179], v[192:195], v[60:63]
	v_mfma_f32_16x16x32_bf16 v[56:59], v[184:187], v[192:195], v[56:59]
	v_mfma_f32_16x16x32_bf16 v[52:55], v[176:179], v[200:203], v[52:55]
	v_mfma_f32_16x16x32_bf16 v[48:51], v[184:187], v[200:203], v[48:51]
	v_mfma_f32_16x16x32_bf16 v[36:39], v[176:179], v[208:211], v[36:39]
	v_mfma_f32_16x16x32_bf16 v[32:35], v[184:187], v[208:211], v[32:35]
	v_mfma_f32_16x16x32_bf16 v[12:15], v[176:179], v[216:219], v[12:15]
	v_mfma_f32_16x16x32_bf16 v[8:11], v[184:187], v[216:219], v[8:11]
	s_setprio 0
	s_barrier
	s_add_u32 s26, s26, 0x80080
	s_addc_u32 s27, s27, 0
	s_add_i32 s28, s28, s35
	v_lshl_add_u64 v[154:155], s[26:27], 0, v[140:141]
	s_mov_b32 m0, s28
	s_nop 0
	global_load_lds_dwordx4 v[154:155], off
	v_lshl_add_u64 v[154:155], s[26:27], 0, v[136:137]
	s_add_i32 m0, s28, 0x2000
	s_nop 0
	global_load_lds_dwordx4 v[154:155], off
	s_waitcnt vmcnt(6)
	s_barrier
	s_setprio 1
	v_mfma_f32_16x16x32_bf16 v[44:47], v[220:223], v[188:191], v[44:47]
	v_mfma_f32_16x16x32_bf16 v[40:43], v[228:231], v[188:191], v[40:43]
	v_mfma_f32_16x16x32_bf16 v[28:31], v[220:223], v[196:199], v[28:31]
	v_mfma_f32_16x16x32_bf16 v[24:27], v[228:231], v[196:199], v[24:27]
	v_mfma_f32_16x16x32_bf16 v[20:23], v[220:223], v[204:207], v[20:23]
	v_mfma_f32_16x16x32_bf16 v[16:19], v[228:231], v[204:207], v[16:19]
	v_mfma_f32_16x16x32_bf16 v[4:7], v[220:223], v[212:215], v[4:7]
	v_mfma_f32_16x16x32_bf16 v[0:3], v[228:231], v[212:215], v[0:3]
	v_mfma_f32_16x16x32_bf16 v[44:47], v[224:227], v[192:195], v[44:47]
	v_mfma_f32_16x16x32_bf16 v[40:43], v[232:235], v[192:195], v[40:43]
	v_mfma_f32_16x16x32_bf16 v[28:31], v[224:227], v[200:203], v[28:31]
	v_mfma_f32_16x16x32_bf16 v[24:27], v[232:235], v[200:203], v[24:27]
	v_mfma_f32_16x16x32_bf16 v[20:23], v[224:227], v[208:211], v[20:23]
	v_mfma_f32_16x16x32_bf16 v[16:19], v[232:235], v[208:211], v[16:19]
	v_mfma_f32_16x16x32_bf16 v[4:7], v[224:227], v[216:219], v[4:7]
	v_mfma_f32_16x16x32_bf16 v[0:3], v[232:235], v[216:219], v[0:3]
	s_setprio 0
	s_add_i32 s67, s67, 2
	s_add_u32 s12, s12, 0x100
	s_addc_u32 s13, s13, 0
	s_add_u32 s65, s65, 0x100
	s_addc_u32 s66, s66, 0
	s_cmp_gt_u32 s67, 29
	s_barrier
	s_cbranch_scc0 .LBB0_80
	s_lshl_b32 s7, s31, 8
	s_add_i32 s7, s7, s47
	v_lshl_or_b32 v156, s30, 8, v172
	s_add_i32 s12, s7, 0xffff8000
	v_or_b32_e32 v176, s7, v161
	v_ashrrev_i32_e32 v157, 31, v156
	s_lshr_b32 s63, s12, 6
	s_ashr_i32 s12, s7, 13
	v_mov_b64_e32 v[178:179], s[14:15]
	s_mul_i32 s26, s12, 0xc80
	v_mad_i64_i32 v[180:181], s[12:13], v176, s58, v[178:179]
	v_lshlrev_b64 v[154:155], 1, v[156:157]
	v_cvt_pk_bf16_f32 v108, v108, v109
	v_cvt_pk_bf16_f32 v109, v110, v111
	v_cvt_pk_bf16_f32 v110, v104, v105
	v_or_b32_e32 v104, 16, v176
	v_cvt_pk_bf16_f32 v92, v92, v93
	v_cvt_pk_bf16_f32 v93, v94, v95
	v_cvt_pk_bf16_f32 v94, v88, v89
	v_or_b32_e32 v88, 32, v176
	v_cvt_pk_bf16_f32 v84, v84, v85
	v_cvt_pk_bf16_f32 v85, v86, v87
	v_cvt_pk_bf16_f32 v87, v82, v83
	v_or_b32_e32 v82, 48, v176
	v_lshl_add_u64 v[180:181], v[180:181], 0, v[154:155]
	v_cvt_pk_bf16_f32 v111, v106, v107
	v_mad_i64_i32 v[104:105], s[12:13], v104, s58, v[178:179]
	v_mad_i64_i32 v[88:89], s[12:13], v88, s58, v[178:179]
	v_cvt_pk_bf16_f32 v86, v80, v81
	v_mad_i64_i32 v[80:81], s[12:13], v82, s58, v[178:179]
	v_bitop3_b32 v83, v176, s60, 48 bitop3:0xc8
	global_store_dwordx4 v[180:181], v[108:111], off offset:256 nt
	v_cvt_pk_bf16_f32 v95, v90, v91
	v_cmp_lt_i32_e32 vcc, s59, v82
	v_lshl_add_u64 v[108:109], v[104:105], 0, v[154:155]
	v_cmp_eq_u32_e64 s[12:13], s60, v83
	global_store_dwordx4 v[108:109], v[92:95], off offset:256 nt
	s_or_b64 s[12:13], vcc, s[12:13]
	s_mul_hi_u32 s25, s63, 0x3200
	v_lshl_add_u64 v[92:93], v[88:89], 0, v[154:155]
	s_mulk_i32 s63, 0x3200
	s_ashr_i32 s27, s26, 31
	v_cvt_pk_bf16_f32 v124, v124, v125
	v_cvt_pk_bf16_f32 v125, v126, v127
	v_cvt_pk_bf16_f32 v126, v120, v121
	v_cvt_pk_bf16_f32 v127, v122, v123
	v_cvt_pk_bf16_f32 v104, v116, v117
	v_cvt_pk_bf16_f32 v105, v118, v119
	v_cvt_pk_bf16_f32 v106, v112, v113
	v_cvt_pk_bf16_f32 v107, v114, v115
	v_cvt_pk_bf16_f32 v88, v100, v101
	v_cvt_pk_bf16_f32 v89, v102, v103
	v_cvt_pk_bf16_f32 v90, v96, v97
	v_cvt_pk_bf16_f32 v91, v98, v99
	global_store_dwordx4 v[92:93], v[84:87], off offset:256 nt
	v_lshl_add_u64 v[80:81], v[80:81], 0, v[154:155]
	s_and_b64 s[28:29], s[8:9], s[12:13]
	v_cmp_gt_i32_e32 vcc, s50, v82
	v_cvt_pk_bf16_f32 v82, v76, v77
	v_cvt_pk_bf16_f32 v83, v78, v79
	v_cvt_pk_bf16_f32 v84, v72, v73
	v_cvt_pk_bf16_f32 v85, v74, v75
	v_add_u32_e32 v144, 0xfffff400, v156
	global_store_dwordx4 v[180:181], v[124:127], off nt
	global_store_dwordx4 v[108:109], v[104:107], off nt
	global_store_dwordx4 v[92:93], v[88:91], off nt
	global_store_dwordx4 v[80:81], v[82:85], off nt
	s_and_saveexec_b64 s[30:31], s[28:29]
	s_cbranch_execz .LBB0_84
	v_cmp_gt_u32_e64 s[12:13], s57, v144
	s_and_b64 exec, exec, s[12:13]
	s_cbranch_execz .LBB0_84
	s_lshl_b64 s[12:13], s[26:27], 2
	s_add_u32 s12, s22, s12
	s_addc_u32 s13, s23, s13
	s_add_u32 s64, s51, s63
	s_addc_u32 s65, s52, s25
	v_mov_b32_e32 v82, s65
	v_mov_b32_e32 v83, s13
	v_cndmask_b32_e32 v83, v82, v83, vcc
	v_mov_b32_e32 v82, s64
	v_mov_b32_e32 v84, s12
	v_cndmask_b32_e32 v82, v82, v84, vcc
	v_lshl_add_u64 v[82:83], v[144:145], 2, v[82:83]
	global_store_dwordx4 v[82:83], v[76:79], off
	global_store_dwordx4 v[82:83], v[72:75], off offset:16
; __device__ __forceinline__ unsigned pk_bf16(float lo, float hi) { const f32x2 v = (f32x2){lo, hi}; const bf16v2 b = __builtin_convertvector(v, bf16v2); return __builtin_bit_cast(unsigned, b); }
;     __device__ __forceinline__ void operator()(const f32x4 (&acc)[2][2][4][2], const pg8::Unit& u, int wr, int wc, int fr, int fq) const {
;     ...
;         for (int ai = 0; ai < 2; ++ai)
; #pragma unroll
;             for (int m = 0; m < 4; ++m) {
;                 const int row = row0 + ai * 128 + m * 16;
;                 bf16_t* rowp = Z + (size_t)row * LDZ + col0;
;                 const bool last = ((row & 63) == 63) && (row >= MP || (row & (SEQ - 1)) == SEQ - 1);
; #pragma unroll
;                 for (int bj = 0; bj < 2; ++bj) {
;                     const f32x4 v0 = acc[ai][bj][m][0], v1 = acc[ai][bj][m][1];
;                     u32x4 w; w.x = pk_bf16(v0[0], v0[1]); w.y = pk_bf16(v0[2], v0[3]); w.z = pk_bf16(v1[0], v1[1]); w.w = pk_bf16(v1[2], v1[3]);
;                     *(u32x4*)(rowp + bj * 128) = w;
;                     if (last) {
;                         const int c = col0 + bj * 128 - ZC_S;
;                         if (c >= 0 && c < NSHIFT) {
;                             float* o = row < MP ? out + O_SHP + (size_t)(row >> 13) * NSHIFT + c : out + O_SHS + (size_t)((row - MP) >> 6) * NSHIFT + c;
;                             *(f32x4*)o = v0; *(f32x4*)(o + 4) = v1;
;                         }
;                     }
;                 }
.LBB0_84:
	s_or_b64 exec, exec, s[30:31]
	s_nop 0
	v_cvt_pk_bf16_f32 v72, v68, v69
	v_cvt_pk_bf16_f32 v73, v70, v71
	v_cvt_pk_bf16_f32 v74, v64, v65
	v_cvt_pk_bf16_f32 v75, v66, v67
	global_store_dwordx4 v[80:81], v[72:75], off offset:256 nt
	s_nop 1
	v_add_u32_e32 v72, 0xfffff480, v156
	s_and_saveexec_b64 s[30:31], s[28:29]
	s_cbranch_execz .LBB0_87
	v_cmp_gt_u32_e64 s[12:13], s57, v72
	s_and_b64 exec, exec, s[12:13]
	s_cbranch_execz .LBB0_87
	s_lshl_b64 s[12:13], s[26:27], 2
	s_add_u32 s12, s22, s12
	s_addc_u32 s13, s23, s13
	s_add_u32 s26, s51, s63
	s_addc_u32 s25, s52, s25
	v_mov_b32_e32 v73, s25
	v_mov_b32_e32 v74, s13
	v_cndmask_b32_e32 v75, v73, v74, vcc
	v_mov_b32_e32 v73, s26
	v_mov_b32_e32 v74, s12
	v_cndmask_b32_e32 v74, v73, v74, vcc
	v_mov_b32_e32 v73, v145
	v_lshl_add_u64 v[74:75], v[72:73], 2, v[74:75]
	global_store_dwordx4 v[74:75], v[68:71], off
	global_store_dwordx4 v[74:75], v[64:67], off offset:16
.LBB0_87:
	s_or_b64 exec, exec, s[30:31]
	v_add_u32_e32 v68, 0x80, v176
	v_mov_b64_e32 v[66:67], s[14:15]
	v_ashrrev_i32_e32 v64, 13, v68
	v_mad_i64_i32 v[68:69], s[12:13], v68, s58, v[66:67]
	v_cvt_pk_bf16_f32 v44, v44, v45
	v_cvt_pk_bf16_f32 v45, v46, v47
	v_cvt_pk_bf16_f32 v46, v40, v41
	v_add_u32_e32 v40, 0x90, v176
	v_cvt_pk_bf16_f32 v28, v28, v29
	v_cvt_pk_bf16_f32 v29, v30, v31
	v_cvt_pk_bf16_f32 v30, v24, v25
	v_add_u32_e32 v24, 0xa0, v176
	v_cvt_pk_bf16_f32 v20, v20, v21
	v_cvt_pk_bf16_f32 v21, v22, v23
	v_cvt_pk_bf16_f32 v23, v18, v19
	v_add_u32_e32 v18, 0xb0, v176
	v_lshl_add_u64 v[68:69], v[68:69], 0, v[154:155]
	v_cvt_pk_bf16_f32 v47, v42, v43
	v_mad_i64_i32 v[40:41], s[12:13], v40, s58, v[66:67]
	v_mad_i64_i32 v[24:25], s[12:13], v24, s58, v[66:67]
	v_cvt_pk_bf16_f32 v22, v16, v17
	v_mad_i64_i32 v[16:17], s[12:13], v18, s58, v[66:67]
	v_and_b32_e32 v18, 0x1fff, v18
	s_addk_i32 s7, 0x8080
	global_store_dwordx4 v[68:69], v[44:47], off offset:256 nt
	v_cvt_pk_bf16_f32 v31, v26, v27
	v_cmp_lt_i32_e32 vcc, s61, v176
	v_lshl_add_u64 v[44:45], v[40:41], 0, v[154:155]
	v_cmp_eq_u32_e64 s[12:13], s60, v18
	s_lshr_b32 s25, s7, 6
	v_mul_i32_i24_e32 v64, 0xc80, v64
	global_store_dwordx4 v[44:45], v[28:31], off offset:256 nt
	s_or_b64 s[12:13], vcc, s[12:13]
	s_mul_hi_u32 s7, s25, 0x3200
	v_lshl_add_u64 v[28:29], v[24:25], 0, v[154:155]
	s_mulk_i32 s25, 0x3200
	v_ashrrev_i32_e32 v65, 31, v64
	v_cvt_pk_bf16_f32 v60, v60, v61
	v_cvt_pk_bf16_f32 v61, v62, v63
	v_cvt_pk_bf16_f32 v62, v56, v57
	v_cvt_pk_bf16_f32 v63, v58, v59
	v_cvt_pk_bf16_f32 v40, v52, v53
	v_cvt_pk_bf16_f32 v41, v54, v55
	v_cvt_pk_bf16_f32 v42, v48, v49
	v_cvt_pk_bf16_f32 v43, v50, v51
	v_cvt_pk_bf16_f32 v24, v36, v37
	v_cvt_pk_bf16_f32 v25, v38, v39
	v_cvt_pk_bf16_f32 v26, v32, v33
	v_cvt_pk_bf16_f32 v27, v34, v35
	global_store_dwordx4 v[28:29], v[20:23], off offset:256 nt
	v_lshl_add_u64 v[16:17], v[16:17], 0, v[154:155]
	s_and_b64 s[26:27], s[8:9], s[12:13]
	v_cmp_gt_i32_e32 vcc, s62, v176
	v_cvt_pk_bf16_f32 v18, v12, v13
	v_cvt_pk_bf16_f32 v19, v14, v15
	v_cvt_pk_bf16_f32 v20, v8, v9
	v_cvt_pk_bf16_f32 v21, v10, v11
	global_store_dwordx4 v[68:69], v[60:63], off nt
	global_store_dwordx4 v[44:45], v[40:43], off nt
	global_store_dwordx4 v[28:29], v[24:27], off nt
	global_store_dwordx4 v[16:17], v[18:21], off nt
	s_and_saveexec_b64 s[28:29], s[26:27]
	s_cbranch_execz .LBB0_90
	v_cmp_gt_u32_e64 s[12:13], s57, v144
	s_and_b64 exec, exec, s[12:13]
	s_cbranch_execz .LBB0_90
	s_add_u32 s12, s51, s25
	s_addc_u32 s13, s52, s7
	v_lshl_add_u64 v[18:19], v[64:65], 2, s[22:23]
	v_mov_b32_e32 v20, s13
	v_cndmask_b32_e32 v19, v20, v19, vcc
	v_mov_b32_e32 v20, s12
	v_cndmask_b32_e32 v18, v20, v18, vcc
	v_lshl_add_u64 v[18:19], v[144:145], 2, v[18:19]
	global_store_dwordx4 v[18:19], v[12:15], off
	global_store_dwordx4 v[18:19], v[8:11], off offset:16
.LBB0_90:
	s_or_b64 exec, exec, s[28:29]
	s_nop 0
	v_cvt_pk_bf16_f32 v8, v4, v5
	v_cvt_pk_bf16_f32 v9, v6, v7
	v_cvt_pk_bf16_f32 v10, v0, v1
	v_cvt_pk_bf16_f32 v11, v2, v3
	global_store_dwordx4 v[16:17], v[8:11], off offset:256 nt
	s_and_saveexec_b64 s[28:29], s[26:27]
	s_cbranch_execz .LBB0_76
	v_cmp_gt_u32_e64 s[12:13], s57, v72
	s_and_b64 exec, exec, s[12:13]
	s_cbranch_execz .LBB0_76
	s_add_u32 s12, s51, s25
	s_addc_u32 s7, s52, s7
	v_lshl_add_u64 v[8:9], v[64:65], 2, s[22:23]
	v_mov_b32_e32 v10, s7
	v_cndmask_b32_e32 v9, v10, v9, vcc
	v_mov_b32_e32 v10, s12
	v_cndmask_b32_e32 v8, v10, v8, vcc
	v_mov_b32_e32 v73, v145
	v_lshl_add_u64 v[8:9], v[72:73], 2, v[8:9]
	global_store_dwordx4 v[8:9], v[4:7], off
	global_store_dwordx4 v[8:9], v[0:3], off offset:16
	s_branch .LBB0_76
